# transposed-v GEMM epilogue: f32 new_cache_v context tiles transposed through wave-private LDS and stored as row-contiguous 16-byte stores (was 128 scattered 4-byte stores per lane)
# baseline (speedup 1.0000x reference)
.LBB0_752:
	s_waitcnt vmcnt(0)
	s_barrier
	v_mbcnt_lo_u32_b32 v232, -1, 0
	v_mbcnt_hi_u32_b32 v232, -1, v232
	v_and_b32_e32 v233, 15, v232
	v_lshrrev_b32_e32 v234, 4, v232
	s_lshl_b32 s98, s94, 14
	v_lshl_add_u32 v235, v234, 4, v233
	v_add_u32_e32 v236, 0, v235
	v_and_b32_e32 v236, 63, v236
	v_lshlrev_b32_e32 v236, 2, v236
	v_lshl_add_u32 v236, v234, 11, v236
	v_add_u32_e32 v236, s98, v236
	v_add_u32_e32 v237, 16, v235
	v_and_b32_e32 v237, 63, v237
	v_lshlrev_b32_e32 v237, 2, v237
	v_lshl_add_u32 v237, v234, 11, v237
	v_add_u32_e32 v237, s98, v237
	v_add_u32_e32 v238, 32, v235
	v_and_b32_e32 v238, 63, v238
	v_lshlrev_b32_e32 v238, 2, v238
	v_lshl_add_u32 v238, v234, 11, v238
	v_add_u32_e32 v238, s98, v238
	v_add_u32_e32 v239, 48, v235
	v_and_b32_e32 v239, 63, v239
	v_lshlrev_b32_e32 v239, 2, v239
	v_lshl_add_u32 v239, v234, 11, v239
	v_add_u32_e32 v239, s98, v239
	v_add_u32_e32 v240, 0, v233
	v_and_b32_e32 v240, 15, v240
	v_lshlrev_b32_e32 v240, 4, v240
	v_lshl_add_u32 v240, v234, 8, v240
	v_add_u32_e32 v240, s98, v240
	v_add_u32_e32 v241, 4, v233
	v_and_b32_e32 v241, 15, v241
	v_lshlrev_b32_e32 v241, 4, v241
	v_lshl_add_u32 v241, v234, 8, v241
	v_add_u32_e32 v241, s98, v241
	v_add_u32_e32 v242, 8, v233
	v_and_b32_e32 v242, 15, v242
	v_lshlrev_b32_e32 v242, 4, v242
	v_lshl_add_u32 v242, v234, 8, v242
	v_add_u32_e32 v242, s98, v242
	v_add_u32_e32 v243, 12, v233
	v_and_b32_e32 v243, 15, v243
	v_lshlrev_b32_e32 v243, 4, v243
	v_lshl_add_u32 v243, v234, 8, v243
	v_add_u32_e32 v243, s98, v243
	v_lshlrev_b32_e32 v244, 4, v232
	v_add_u32_e32 v245, 0x1000, v244
	s_mov_b32 s99, 0
	s_lshl_b32 s21, s66, 8
	v_lshl_add_u32 v172, s8, 8, v162
	s_add_i32 s21, s21, s76
	s_movk_i32 s8, 0xfff
	v_add_u32_e32 v140, 0xfffff000, v172
	v_and_b32_e32 v171, 0x7f8, v172
	s_ashr_i32 s61, s21, 6
	v_cmp_lt_i32_e32 vcc, s8, v172
	v_lshrrev_b32_e32 v170, 8, v140
	v_lshlrev_b32_e32 v140, 1, v171
	v_cvt_pk_bf16_f32 v128, v124, v125
	v_cvt_pk_bf16_f32 v129, v126, v127
	v_cvt_pk_bf16_f32 v130, v120, v121
	v_cvt_pk_bf16_f32 v131, v122, v123
	s_and_saveexec_b64 s[8:9], vcc
	s_xor_b64 s[8:9], exec, s[8:9]
	s_cbranch_execz .LBB0_754
	v_and_b32_e32 v171, 0xfffff8, v170
	v_add_u32_e32 v171, s61, v171
	v_lshl_or_b32 v171, v171, 6, v160
	v_mov_b64_e32 v[174:175], s[50:51]
	v_mad_i64_i32 v[174:175], s[66:67], v171, s82, v[174:175]
	v_lshl_add_u64 v[174:175], v[174:175], 0, v[140:141]
	global_store_dwordx4 v[174:175], v[128:131], off
.LBB0_754:
	s_or_saveexec_b64 s[8:9], s[8:9]
	v_ashrrev_i32_e32 v171, 5, v172
	v_and_b32_e32 v171, -8, v171
	s_xor_b64 exec, exec, s[8:9]
	s_cbranch_execz .LBB0_756
	v_add_u32_e32 v173, s61, v171
	v_lshl_or_b32 v174, v173, 6, v160
	v_mad_i64_i32 v[174:175], s[66:67], v174, s83, v[142:143]
	global_store_dwordx4 v[174:175], v[128:131], off
	s_nop 1
	v_lshl_or_b32 v128, v173, 8, v166
	v_ashrrev_i32_e32 v129, 31, v128
	v_lshlrev_b64 v[128:129], 8, v[128:129]
	v_lshl_add_u64 v[128:129], v[144:145], 0, v[128:129]
	s_nop 0
	v_readfirstlane_b32 s98, v128
	v_readfirstlane_b32 s99, v129
	ds_write_b32 v236, v124
	ds_write_b32 v236, v120 offset:1024
	ds_write_b32 v236, v125 offset:256
	ds_write_b32 v236, v121 offset:1280
	ds_write_b32 v236, v126 offset:512
	ds_write_b32 v236, v122 offset:1536
	ds_write_b32 v236, v127 offset:768
	ds_write_b32 v236, v123 offset:1792

.LBB0_758:
	s_or_saveexec_b64 s[66:67], s[66:67]
	v_and_b32_e32 v129, 0xf8, v126
	v_ashrrev_i32_e32 v125, 5, v126
	v_and_b32_e32 v130, -8, v125
	v_lshlrev_b32_e32 v126, 1, v129
	s_xor_b64 exec, exec, s[66:67]
	s_cbranch_execz .LBB0_760
	v_add_u32_e32 v125, s61, v130
	v_lshl_or_b32 v127, v125, 6, v160
	v_mov_b64_e32 v[172:173], s[38:39]
	v_mad_i64_i32 v[172:173], s[68:69], v127, s83, v[172:173]
	v_mov_b32_e32 v127, v141
	v_lshl_add_u64 v[172:173], v[172:173], 0, v[126:127]
	global_store_dwordx4 v[172:173], v[120:123], off
	s_nop 1
	v_lshl_or_b32 v120, v125, 8, v129
	v_ashrrev_i32_e32 v121, 31, v120
	v_lshlrev_b64 v[120:121], 8, v[120:121]
	v_lshl_add_u64 v[120:121], v[144:145], 0, v[120:121]
	s_nop 0
	v_readfirstlane_b32 s100, v120
	v_readfirstlane_b32 s101, v121
	ds_write_b32 v236, v116 offset:8192
	ds_write_b32 v236, v112 offset:9216
	ds_write_b32 v236, v117 offset:8448
	ds_write_b32 v236, v113 offset:9472
	ds_write_b32 v236, v118 offset:8704
	ds_write_b32 v236, v114 offset:9728
	ds_write_b32 v236, v119 offset:8960
	ds_write_b32 v236, v115 offset:9984

.LBB0_762:
	s_andn2_saveexec_b64 s[66:67], s[66:67]
	s_cbranch_execz .LBB0_764
	v_add_u32_e32 v118, s61, v171
	v_lshl_or_b32 v116, v118, 6, v163
	v_mad_i64_i32 v[116:117], s[68:69], v116, s83, v[142:143]
	global_store_dwordx4 v[116:117], v[112:115], off
	s_nop 1
	v_lshl_or_b32 v112, v118, 8, v166
	v_ashrrev_i32_e32 v113, 31, v112
	v_lshlrev_b64 v[112:113], 8, v[112:113]
	v_lshl_add_u64 v[112:113], v[146:147], 0, v[112:113]
	ds_write_b32 v237, v108
	ds_write_b32 v237, v104 offset:1024
	ds_write_b32 v237, v109 offset:256
	ds_write_b32 v237, v105 offset:1280
	ds_write_b32 v237, v110 offset:512
	ds_write_b32 v237, v106 offset:1536
	ds_write_b32 v237, v111 offset:768
	ds_write_b32 v237, v107 offset:1792

.LBB0_766:
	s_andn2_saveexec_b64 s[66:67], s[66:67]
	s_cbranch_execz .LBB0_768
	v_add_u32_e32 v110, s61, v130
	v_lshl_or_b32 v111, v110, 6, v163
	v_mov_b64_e32 v[108:109], s[38:39]
	v_mad_i64_i32 v[108:109], s[68:69], v111, s83, v[108:109]
	v_mov_b32_e32 v127, v141
	v_lshl_add_u64 v[108:109], v[108:109], 0, v[126:127]
	global_store_dwordx4 v[108:109], v[104:107], off
	s_nop 1
	v_lshl_or_b32 v104, v110, 8, v129
	v_ashrrev_i32_e32 v105, 31, v104
	v_lshlrev_b64 v[104:105], 8, v[104:105]
	v_lshl_add_u64 v[104:105], v[146:147], 0, v[104:105]
	ds_write_b32 v237, v100 offset:8192
	ds_write_b32 v237, v96 offset:9216
	ds_write_b32 v237, v101 offset:8448
	ds_write_b32 v237, v97 offset:9472
	ds_write_b32 v237, v102 offset:8704
	ds_write_b32 v237, v98 offset:9728
	ds_write_b32 v237, v103 offset:8960
	ds_write_b32 v237, v99 offset:9984

.LBB0_770:
	s_andn2_saveexec_b64 s[66:67], s[66:67]
	s_cbranch_execz .LBB0_772
	v_add_u32_e32 v102, s61, v171
	v_lshl_or_b32 v100, v102, 6, v164
	v_mad_i64_i32 v[100:101], s[68:69], v100, s83, v[142:143]
	global_store_dwordx4 v[100:101], v[96:99], off
	s_nop 1
	v_lshl_or_b32 v96, v102, 8, v166
	v_ashrrev_i32_e32 v97, 31, v96
	v_lshlrev_b64 v[96:97], 8, v[96:97]
	v_lshl_add_u64 v[96:97], v[148:149], 0, v[96:97]
	ds_write_b32 v238, v92
	ds_write_b32 v238, v88 offset:1024
	ds_write_b32 v238, v93 offset:256
	ds_write_b32 v238, v89 offset:1280
	ds_write_b32 v238, v94 offset:512
	ds_write_b32 v238, v90 offset:1536
	ds_write_b32 v238, v95 offset:768
	ds_write_b32 v238, v91 offset:1792

.LBB0_774:
	s_andn2_saveexec_b64 s[66:67], s[66:67]
	s_cbranch_execz .LBB0_776
	v_add_u32_e32 v94, s61, v130
	v_lshl_or_b32 v95, v94, 6, v164
	v_mov_b64_e32 v[92:93], s[38:39]
	v_mad_i64_i32 v[92:93], s[68:69], v95, s83, v[92:93]
	v_mov_b32_e32 v127, v141
	v_lshl_add_u64 v[92:93], v[92:93], 0, v[126:127]
	global_store_dwordx4 v[92:93], v[88:91], off
	s_nop 1
	v_lshl_or_b32 v88, v94, 8, v129
	v_ashrrev_i32_e32 v89, 31, v88
	v_lshlrev_b64 v[88:89], 8, v[88:89]
	v_lshl_add_u64 v[88:89], v[148:149], 0, v[88:89]
	ds_write_b32 v238, v84 offset:8192
	ds_write_b32 v238, v80 offset:9216
	ds_write_b32 v238, v85 offset:8448
	ds_write_b32 v238, v81 offset:9472
	ds_write_b32 v238, v86 offset:8704
	ds_write_b32 v238, v82 offset:9728
	ds_write_b32 v238, v87 offset:8960
	ds_write_b32 v238, v83 offset:9984

.LBB0_778:
	s_andn2_saveexec_b64 s[66:67], s[66:67]
	s_cbranch_execz .LBB0_780
	v_add_u32_e32 v86, s61, v171
	v_lshl_or_b32 v84, v86, 6, v165
	v_mad_i64_i32 v[84:85], s[68:69], v84, s83, v[142:143]
	global_store_dwordx4 v[84:85], v[80:83], off
	s_nop 1
	v_lshl_or_b32 v80, v86, 8, v166
	v_ashrrev_i32_e32 v81, 31, v80
	v_lshlrev_b64 v[80:81], 8, v[80:81]
	v_lshl_add_u64 v[80:81], v[150:151], 0, v[80:81]
	ds_write_b32 v239, v76
	ds_write_b32 v239, v72 offset:1024
	ds_write_b32 v239, v77 offset:256
	ds_write_b32 v239, v73 offset:1280
	ds_write_b32 v239, v78 offset:512
	ds_write_b32 v239, v74 offset:1536
	ds_write_b32 v239, v79 offset:768
	ds_write_b32 v239, v75 offset:1792

.LBB0_782:
	s_andn2_saveexec_b64 s[66:67], s[66:67]
	s_cbranch_execz .LBB0_784
	v_add_u32_e32 v78, s61, v130
	v_lshl_or_b32 v79, v78, 6, v165
	v_mov_b64_e32 v[76:77], s[38:39]
	v_mad_i64_i32 v[76:77], s[68:69], v79, s83, v[76:77]
	v_mov_b32_e32 v127, v141
	v_lshl_add_u64 v[76:77], v[76:77], 0, v[126:127]
	global_store_dwordx4 v[76:77], v[72:75], off
	s_nop 1
	v_lshl_or_b32 v72, v78, 8, v129
	v_ashrrev_i32_e32 v73, 31, v72
	v_lshlrev_b64 v[72:73], 8, v[72:73]
	v_lshl_add_u64 v[72:73], v[150:151], 0, v[72:73]
	ds_write_b32 v239, v68 offset:8192
	ds_write_b32 v239, v64 offset:9216
	ds_write_b32 v239, v69 offset:8448
	ds_write_b32 v239, v65 offset:9472
	ds_write_b32 v239, v70 offset:8704
	ds_write_b32 v239, v66 offset:9728
	ds_write_b32 v239, v71 offset:8960
	ds_write_b32 v239, v67 offset:9984
.LBB0_784:
	s_or_b64 exec, exec, s[66:67]
	s_cmp_eq_u32 s99, 0
	s_cbranch_scc1 .Lvt_nf_a
	s_waitcnt lgkmcnt(0)
	ds_read_b128 v[176:179], v240
	ds_read_b128 v[180:183], v240 offset:1024
	ds_read_b128 v[184:187], v241 offset:2048
	ds_read_b128 v[188:191], v241 offset:3072
	ds_read_b128 v[192:195], v242 offset:4096
	ds_read_b128 v[196:199], v242 offset:5120
	ds_read_b128 v[200:203], v243 offset:6144
	ds_read_b128 v[204:207], v243 offset:7168
	s_waitcnt lgkmcnt(0)
	global_store_dwordx4 v244, v[176:179], s[98:99]
	global_store_dwordx4 v244, v[180:183], s[98:99] offset:1024
	global_store_dwordx4 v244, v[184:187], s[98:99] offset:2048
	global_store_dwordx4 v244, v[188:191], s[98:99] offset:3072
	global_store_dwordx4 v245, v[192:195], s[98:99]
	global_store_dwordx4 v245, v[196:199], s[98:99] offset:1024
	global_store_dwordx4 v245, v[200:203], s[98:99] offset:2048
	global_store_dwordx4 v245, v[204:207], s[98:99] offset:3072
	ds_read_b128 v[176:179], v240 offset:8192
	ds_read_b128 v[180:183], v240 offset:9216
	ds_read_b128 v[184:187], v241 offset:10240
	ds_read_b128 v[188:191], v241 offset:11264
	ds_read_b128 v[192:195], v242 offset:12288
	ds_read_b128 v[196:199], v242 offset:13312
	ds_read_b128 v[200:203], v243 offset:14336
	ds_read_b128 v[204:207], v243 offset:15360
	s_waitcnt lgkmcnt(0)
	global_store_dwordx4 v244, v[176:179], s[100:101]
	global_store_dwordx4 v244, v[180:183], s[100:101] offset:1024
	global_store_dwordx4 v244, v[184:187], s[100:101] offset:2048
	global_store_dwordx4 v244, v[188:191], s[100:101] offset:3072
	global_store_dwordx4 v245, v[192:195], s[100:101]
	global_store_dwordx4 v245, v[196:199], s[100:101] offset:1024
	global_store_dwordx4 v245, v[200:203], s[100:101] offset:2048
	global_store_dwordx4 v245, v[204:207], s[100:101] offset:3072
	s_mov_b32 s99, 0
.Lvt_nf_a:
	s_addk_i32 s21, 0x80
	s_ashr_i32 s21, s21, 6
	v_cvt_pk_bf16_f32 v64, v60, v61
	v_cvt_pk_bf16_f32 v65, v62, v63
	v_cvt_pk_bf16_f32 v66, v56, v57
	v_cvt_pk_bf16_f32 v67, v58, v59
	s_and_saveexec_b64 s[66:67], vcc
	s_xor_b64 s[66:67], exec, s[66:67]
	s_cbranch_execz .LBB0_786
	v_and_b32_e32 v68, 0xfffff8, v170
	v_add_u32_e32 v68, s21, v68
	v_lshl_or_b32 v70, v68, 6, v160
	v_mov_b64_e32 v[68:69], s[50:51]
	v_mad_i64_i32 v[68:69], s[68:69], v70, s82, v[68:69]
	v_lshl_add_u64 v[68:69], v[68:69], 0, v[140:141]
	global_store_dwordx4 v[68:69], v[64:67], off
.LBB0_786:
	s_andn2_saveexec_b64 s[66:67], s[66:67]
	s_cbranch_execz .LBB0_788
	v_add_u32_e32 v70, s21, v171
	v_lshl_or_b32 v68, v70, 6, v160
	v_mad_i64_i32 v[68:69], s[68:69], v68, s83, v[142:143]
	global_store_dwordx4 v[68:69], v[64:67], off
	s_nop 1
	v_lshl_or_b32 v64, v70, 8, v166
	v_ashrrev_i32_e32 v65, 31, v64
	v_lshlrev_b64 v[64:65], 8, v[64:65]
	v_lshl_add_u64 v[64:65], v[144:145], 0, v[64:65]
	s_nop 0
	v_readfirstlane_b32 s98, v64
	v_readfirstlane_b32 s99, v65
	ds_write_b32 v236, v60
	ds_write_b32 v236, v56 offset:1024
	ds_write_b32 v236, v61 offset:256
	ds_write_b32 v236, v57 offset:1280
	ds_write_b32 v236, v62 offset:512
	ds_write_b32 v236, v58 offset:1536
	ds_write_b32 v236, v63 offset:768
	ds_write_b32 v236, v59 offset:1792

.LBB0_790:
	s_andn2_saveexec_b64 s[66:67], s[66:67]
	s_cbranch_execz .LBB0_792
	v_add_u32_e32 v62, s21, v130
	v_lshl_or_b32 v63, v62, 6, v160
	v_mov_b64_e32 v[60:61], s[38:39]
	v_mad_i64_i32 v[60:61], s[68:69], v63, s83, v[60:61]
	v_mov_b32_e32 v127, v141
	v_lshl_add_u64 v[60:61], v[60:61], 0, v[126:127]
	global_store_dwordx4 v[60:61], v[56:59], off
	s_nop 1
	v_lshl_or_b32 v56, v62, 8, v129
	v_ashrrev_i32_e32 v57, 31, v56
	v_lshlrev_b64 v[56:57], 8, v[56:57]
	v_lshl_add_u64 v[56:57], v[144:145], 0, v[56:57]
	s_nop 0
	v_readfirstlane_b32 s100, v56
	v_readfirstlane_b32 s101, v57
	ds_write_b32 v236, v52 offset:8192
	ds_write_b32 v236, v48 offset:9216
	ds_write_b32 v236, v53 offset:8448
	ds_write_b32 v236, v49 offset:9472
	ds_write_b32 v236, v54 offset:8704
	ds_write_b32 v236, v50 offset:9728
	ds_write_b32 v236, v55 offset:8960
	ds_write_b32 v236, v51 offset:9984

.LBB0_794:
	s_andn2_saveexec_b64 s[66:67], s[66:67]
	s_cbranch_execz .LBB0_796
	v_add_u32_e32 v54, s21, v171
	v_lshl_or_b32 v52, v54, 6, v163
	v_mad_i64_i32 v[52:53], s[68:69], v52, s83, v[142:143]
	global_store_dwordx4 v[52:53], v[48:51], off
	s_nop 1
	v_lshl_or_b32 v48, v54, 8, v166
	v_ashrrev_i32_e32 v49, 31, v48
	v_lshlrev_b64 v[48:49], 8, v[48:49]
	v_lshl_add_u64 v[48:49], v[146:147], 0, v[48:49]
	ds_write_b32 v237, v44
	ds_write_b32 v237, v40 offset:1024
	ds_write_b32 v237, v45 offset:256
	ds_write_b32 v237, v41 offset:1280
	ds_write_b32 v237, v46 offset:512
	ds_write_b32 v237, v42 offset:1536
	ds_write_b32 v237, v47 offset:768
	ds_write_b32 v237, v43 offset:1792

.LBB0_798:
	s_andn2_saveexec_b64 s[66:67], s[66:67]
	s_cbranch_execz .LBB0_800
	v_add_u32_e32 v46, s21, v130
	v_lshl_or_b32 v47, v46, 6, v163
	v_mov_b64_e32 v[44:45], s[38:39]
	v_mad_i64_i32 v[44:45], s[68:69], v47, s83, v[44:45]
	v_mov_b32_e32 v127, v141
	v_lshl_add_u64 v[44:45], v[44:45], 0, v[126:127]
	global_store_dwordx4 v[44:45], v[40:43], off
	s_nop 1
	v_lshl_or_b32 v40, v46, 8, v129
	v_ashrrev_i32_e32 v41, 31, v40
	v_lshlrev_b64 v[40:41], 8, v[40:41]
	v_lshl_add_u64 v[40:41], v[146:147], 0, v[40:41]
	ds_write_b32 v237, v36 offset:8192
	ds_write_b32 v237, v32 offset:9216
	ds_write_b32 v237, v37 offset:8448
	ds_write_b32 v237, v33 offset:9472
	ds_write_b32 v237, v38 offset:8704
	ds_write_b32 v237, v34 offset:9728
	ds_write_b32 v237, v39 offset:8960
	ds_write_b32 v237, v35 offset:9984

.LBB0_802:
	s_andn2_saveexec_b64 s[66:67], s[66:67]
	s_cbranch_execz .LBB0_804
	v_add_u32_e32 v38, s21, v171
	v_lshl_or_b32 v36, v38, 6, v164
	v_mad_i64_i32 v[36:37], s[68:69], v36, s83, v[142:143]
	global_store_dwordx4 v[36:37], v[32:35], off
	s_nop 1
	v_lshl_or_b32 v32, v38, 8, v166
	v_ashrrev_i32_e32 v33, 31, v32
	v_lshlrev_b64 v[32:33], 8, v[32:33]
	v_lshl_add_u64 v[32:33], v[148:149], 0, v[32:33]
	ds_write_b32 v238, v28
	ds_write_b32 v238, v24 offset:1024
	ds_write_b32 v238, v29 offset:256
	ds_write_b32 v238, v25 offset:1280
	ds_write_b32 v238, v30 offset:512
	ds_write_b32 v238, v26 offset:1536
	ds_write_b32 v238, v31 offset:768
	ds_write_b32 v238, v27 offset:1792

.LBB0_806:
	s_andn2_saveexec_b64 s[66:67], s[66:67]
	s_cbranch_execz .LBB0_808
	v_add_u32_e32 v30, s21, v130
	v_lshl_or_b32 v31, v30, 6, v164
	v_mov_b64_e32 v[28:29], s[38:39]
	v_mad_i64_i32 v[28:29], s[68:69], v31, s83, v[28:29]
	v_mov_b32_e32 v127, v141
	v_lshl_add_u64 v[28:29], v[28:29], 0, v[126:127]
	global_store_dwordx4 v[28:29], v[24:27], off
	s_nop 1
	v_lshl_or_b32 v24, v30, 8, v129
	v_ashrrev_i32_e32 v25, 31, v24
	v_lshlrev_b64 v[24:25], 8, v[24:25]
	v_lshl_add_u64 v[24:25], v[148:149], 0, v[24:25]
	ds_write_b32 v238, v20 offset:8192
	ds_write_b32 v238, v16 offset:9216
	ds_write_b32 v238, v21 offset:8448
	ds_write_b32 v238, v17 offset:9472
	ds_write_b32 v238, v22 offset:8704
	ds_write_b32 v238, v18 offset:9728
	ds_write_b32 v238, v23 offset:8960
	ds_write_b32 v238, v19 offset:9984

.LBB0_810:
	s_andn2_saveexec_b64 s[66:67], s[66:67]
	s_cbranch_execz .LBB0_812
	v_add_u32_e32 v22, s21, v171
	v_lshl_or_b32 v20, v22, 6, v165
	v_mad_i64_i32 v[20:21], s[68:69], v20, s83, v[142:143]
	global_store_dwordx4 v[20:21], v[16:19], off
	s_nop 1
	v_lshl_or_b32 v16, v22, 8, v166
	v_ashrrev_i32_e32 v17, 31, v16
	v_lshlrev_b64 v[16:17], 8, v[16:17]
	v_lshl_add_u64 v[16:17], v[150:151], 0, v[16:17]
	ds_write_b32 v239, v12
	ds_write_b32 v239, v8 offset:1024
	ds_write_b32 v239, v13 offset:256
	ds_write_b32 v239, v9 offset:1280
	ds_write_b32 v239, v14 offset:512
	ds_write_b32 v239, v10 offset:1536
	ds_write_b32 v239, v15 offset:768
	ds_write_b32 v239, v11 offset:1792

.LBB0_816:
	v_add_u32_e32 v14, s21, v130
	v_lshl_or_b32 v15, v14, 6, v165
	v_mov_b64_e32 v[12:13], s[38:39]
	v_mad_i64_i32 v[12:13], s[66:67], v15, s83, v[12:13]
	v_mov_b32_e32 v127, v141
	v_lshl_add_u64 v[12:13], v[12:13], 0, v[126:127]
	global_store_dwordx4 v[12:13], v[8:11], off
	s_nop 1
	v_lshl_or_b32 v8, v14, 8, v129
	v_ashrrev_i32_e32 v9, 31, v8
	v_lshlrev_b64 v[8:9], 8, v[8:9]
	v_lshl_add_u64 v[8:9], v[150:151], 0, v[8:9]
	ds_write_b32 v239, v4 offset:8192
	ds_write_b32 v239, v0 offset:9216
	ds_write_b32 v239, v5 offset:8448
	ds_write_b32 v239, v1 offset:9472
	ds_write_b32 v239, v6 offset:8704
	ds_write_b32 v239, v2 offset:9728
	ds_write_b32 v239, v7 offset:8960
	ds_write_b32 v239, v3 offset:9984
	s_or_b64 exec, exec, s[8:9]
	s_cmp_eq_u32 s99, 0
	s_cbranch_scc1 .Lvt_nf_b
	s_waitcnt lgkmcnt(0)
	ds_read_b128 v[176:179], v240
	ds_read_b128 v[180:183], v240 offset:1024
	ds_read_b128 v[184:187], v241 offset:2048
	ds_read_b128 v[188:191], v241 offset:3072
	ds_read_b128 v[192:195], v242 offset:4096
	ds_read_b128 v[196:199], v242 offset:5120
	ds_read_b128 v[200:203], v243 offset:6144
	ds_read_b128 v[204:207], v243 offset:7168
	s_waitcnt lgkmcnt(0)
	global_store_dwordx4 v244, v[176:179], s[98:99]
	global_store_dwordx4 v244, v[180:183], s[98:99] offset:1024
	global_store_dwordx4 v244, v[184:187], s[98:99] offset:2048
	global_store_dwordx4 v244, v[188:191], s[98:99] offset:3072
	global_store_dwordx4 v245, v[192:195], s[98:99]
	global_store_dwordx4 v245, v[196:199], s[98:99] offset:1024
	global_store_dwordx4 v245, v[200:203], s[98:99] offset:2048
	global_store_dwordx4 v245, v[204:207], s[98:99] offset:3072
	ds_read_b128 v[176:179], v240 offset:8192
	ds_read_b128 v[180:183], v240 offset:9216
	ds_read_b128 v[184:187], v241 offset:10240
	ds_read_b128 v[188:191], v241 offset:11264
	ds_read_b128 v[192:195], v242 offset:12288
	ds_read_b128 v[196:199], v242 offset:13312
	ds_read_b128 v[200:203], v243 offset:14336
	ds_read_b128 v[204:207], v243 offset:15360
	s_waitcnt lgkmcnt(0)
	global_store_dwordx4 v244, v[176:179], s[100:101]
	global_store_dwordx4 v244, v[180:183], s[100:101] offset:1024
	global_store_dwordx4 v244, v[184:187], s[100:101] offset:2048
	global_store_dwordx4 v244, v[188:191], s[100:101] offset:3072
	global_store_dwordx4 v245, v[192:195], s[100:101]
	global_store_dwordx4 v245, v[196:199], s[100:101] offset:1024
	global_store_dwordx4 v245, v[200:203], s[100:101] offset:2048
	global_store_dwordx4 v245, v[204:207], s[100:101] offset:3072
	s_mov_b32 s99, 0
.Lvt_nf_b:
	s_andn2_b64 vcc, exec, s[6:7]
	s_mov_b64 s[6:7], -1
	s_cbranch_vccnz .LBB0_745

	.amdhsa_kernel _Z14fwd_megakernel4Args
		.amdhsa_group_segment_fixed_size 0
		.amdhsa_private_segment_fixed_size 0
		.amdhsa_kernarg_size 544
		.amdhsa_user_sgpr_count 2
		.amdhsa_user_sgpr_dispatch_ptr 0
		.amdhsa_user_sgpr_queue_ptr 0
		.amdhsa_user_sgpr_kernarg_segment_ptr 1
		.amdhsa_user_sgpr_dispatch_id 0
		.amdhsa_user_sgpr_kernarg_preload_length 0
		.amdhsa_user_sgpr_kernarg_preload_offset 0
		.amdhsa_user_sgpr_private_segment_size 0
		.amdhsa_uses_dynamic_stack 0
		.amdhsa_enable_private_segment 0
		.amdhsa_system_sgpr_workgroup_id_x 1
		.amdhsa_system_sgpr_workgroup_id_y 0
		.amdhsa_system_sgpr_workgroup_id_z 0
		.amdhsa_system_sgpr_workgroup_info 0
		.amdhsa_system_vgpr_workitem_id 2
		.amdhsa_next_free_vgpr 248
		.amdhsa_next_free_sgpr 102
		.amdhsa_accum_offset 248
		.amdhsa_reserve_vcc 1
		.amdhsa_float_round_mode_32 0
		.amdhsa_float_round_mode_16_64 0
		.amdhsa_float_denorm_mode_32 3
		.amdhsa_float_denorm_mode_16_64 3
		.amdhsa_dx10_clamp 1
		.amdhsa_ieee_mode 1
		.amdhsa_fp16_overflow 0
		.amdhsa_tg_split 0
		.amdhsa_exception_fp_ieee_invalid_op 0
		.amdhsa_exception_fp_denorm_src 0
		.amdhsa_exception_fp_ieee_div_zero 0
		.amdhsa_exception_fp_ieee_overflow 0
		.amdhsa_exception_fp_ieee_underflow 0
		.amdhsa_exception_fp_ieee_inexact 0
		.amdhsa_exception_int_div_zero 0
	.end_amdhsa_kernel

amdhsa.kernels:
  - .agpr_count:     0
    .args:
      - .offset:         0
        .size:           288
        .value_kind:     by_value
      - .offset:         288
        .size:           4
        .value_kind:     hidden_block_count_x
      - .offset:         292
        .size:           4
        .value_kind:     hidden_block_count_y
      - .offset:         296
        .size:           4
        .value_kind:     hidden_block_count_z
      - .offset:         300
        .size:           2
        .value_kind:     hidden_group_size_x
      - .offset:         302
        .size:           2
        .value_kind:     hidden_group_size_y
      - .offset:         304
        .size:           2
        .value_kind:     hidden_group_size_z
      - .offset:         306
        .size:           2
        .value_kind:     hidden_remainder_x
      - .offset:         308
        .size:           2
        .value_kind:     hidden_remainder_y
      - .offset:         310
        .size:           2
        .value_kind:     hidden_remainder_z
      - .offset:         328
        .size:           8
        .value_kind:     hidden_global_offset_x
      - .offset:         336
        .size:           8
        .value_kind:     hidden_global_offset_y
      - .offset:         344
        .size:           8
        .value_kind:     hidden_global_offset_z
      - .offset:         352
        .size:           2
        .value_kind:     hidden_grid_dims
      - .offset:         376
        .size:           8
        .value_kind:     hidden_multigrid_sync_arg
      - .offset:         408
        .size:           4
        .value_kind:     hidden_dynamic_lds_size
    .group_segment_fixed_size: 0
    .kernarg_segment_align: 8
    .kernarg_segment_size: 544
    .language:       OpenCL C
    .language_version:
      - 2
      - 0
    .max_flat_workgroup_size: 512
    .name:           _Z14fwd_megakernel4Args
    .private_segment_fixed_size: 0
    .sgpr_count:     108
    .sgpr_spill_count: 27
    .symbol:         _Z14fwd_megakernel4Args.kd
    .uniform_work_group_size: 1
    .uses_dynamic_stack: false
    .vgpr_count:     248
    .vgpr_spill_count: 0
    .wavefront_size: 64
